# P0: workgroups 0..127 also hand their sample RMSNorm rows (5th step, waves 0-3) to waves 4-7 of workgroup bx+128
# baseline (speedup 1.0000x reference)
.LBB0_114:
	v_readlane_b32 s0, v248, 6
	v_readlane_b32 s1, v248, 7
	v_readlane_b32 s0, v248, 39
	v_mov_b32_e32 v67, 0
	v_lshlrev_b32_e32 v66, 4, v206
	v_readlane_b32 s1, v248, 40
	v_readlane_b32 s2, v248, 8
	v_readlane_b32 s3, v248, 9
	v_lshl_add_u64 v[68:69], s[0:1], 0, v[66:67]
	s_mov_b64 s[0:1], 0x1000
	v_lshl_add_u64 v[70:71], v[68:69], 0, s[0:1]
	s_mov_b64 s[0:1], 0x1400
	v_lshl_add_u64 v[72:73], v[68:69], 0, s[0:1]
	s_mov_b64 s[0:1], 0x1800
	v_lshl_add_u64 v[74:75], v[68:69], 0, s[0:1]
	s_mov_b64 s[0:1], 0x1c00
	v_lshl_add_u64 v[76:77], v[68:69], 0, s[0:1]
	s_mov_b64 s[0:1], 0x2000
	v_lshl_add_u64 v[78:79], v[68:69], 0, s[0:1]
	s_mov_b64 s[0:1], 0x2400
	v_lshl_add_u64 v[80:81], v[68:69], 0, s[0:1]
	s_mov_b64 s[0:1], 0x2800
	v_lshl_add_u64 v[82:83], v[68:69], 0, s[0:1]
	s_mov_b64 s[0:1], 0x2c00
	s_add_u32 s18, s2, 0x2a0000
	v_lshl_add_u64 v[84:85], v[68:69], 0, s[0:1]
	s_mov_b64 s[0:1], 0x3000
	s_addc_u32 s19, s3, 0
	v_lshl_add_u64 v[86:87], v[68:69], 0, s[0:1]
	s_mov_b64 s[0:1], 0x3400
	v_lshl_add_u64 v[88:89], v[68:69], 0, s[0:1]
	s_mov_b64 s[0:1], 0x3800
	s_cmp_eq_u64 s[2:3], 0
	v_readlane_b32 s2, v248, 22
	v_lshl_add_u64 v[90:91], v[68:69], 0, s[0:1]
	s_mov_b64 s[0:1], 0x3c00
	v_lshlrev_b32_e32 v66, 2, v206
	v_readlane_b32 s3, v248, 23
	v_readlane_b32 s6, v248, 3
	v_lshl_add_u64 v[92:93], v[68:69], 0, s[0:1]
	s_cselect_b64 s[0:1], -1, 0
	v_lshl_add_u64 v[94:95], s[2:3], 0, v[66:67]
	s_waitcnt lgkmcnt(0)
	s_lshl_b32 s2, s95, 5
	s_min_i32 s3, s6, 16
	s_add_i32 s2, s66, s2
	s_addk_i32 s3, 0x2400
	v_readlane_b32 s7, v248, 0
	s_cmp_eq_u32 s7, 7
	s_cselect_b32 s3, s3, 0x2410
	s_lshl_b32 s6, s6, 2
	s_add_i32 s6, s7, s6
	s_addk_i32 s6, 0x2000
	v_mbcnt_lo_u32_b32 v2, -1, 0
	s_cmp_lt_i32 s7, 4
	v_mbcnt_hi_u32_b32 v102, -1, v2
	s_cselect_b32 s3, s6, s3
	s_cmpk_eq_i32 s95, 0x100
	v_and_b32_e32 v2, 64, v102
	s_mov_b32 s9, 0
	v_cmp_eq_u32_e64 s[4:5], 0, v206
	s_movk_i32 s20, 0x2000
	s_cselect_b32 s21, s3, s2
	s_add_i32 s22, s66, s59
	v_lshlrev_b32_e32 v66, 4, v206
	s_movk_i32 s23, 0x1000
	s_movk_i32 s26, 0x3000
	v_mov_b32_e32 v1, 0x358637bd
	s_mov_b32 s27, 0xf800000
	v_mov_b32_e32 v101, 0x260
	v_lshlrev_b32_e32 v96, 3, v206
	s_movk_i32 s28, 0x7fff
	s_mov_b32 s29, 0x42fe0000
	v_add_u32_e32 v103, 64, v2
	v_xor_b32_e32 v104, 1, v102
	v_xor_b32_e32 v105, 2, v102
	v_xor_b32_e32 v106, 4, v102
	v_xor_b32_e32 v107, 8, v102
	v_xor_b32_e32 v108, 16, v102
	v_xor_b32_e32 v109, 32, v102
	v_mov_b32_e32 v110, 1
	s_mov_b32 s30, 0
	s_mov_b32 s10, s66
	v_readlane_b32 s98, v248, 32
	v_readlane_b32 s99, v248, 0
	v_readlane_b32 s100, v248, 3
	s_nop 0
	s_cmp_lt_u32 s98, 0x80
	s_cbranch_scc0 .Lr5_high
	s_cmp_lt_u32 s99, 4
	s_cbranch_scc0 .Lr5_done
	s_movk_i32 s21, 0x2410
	s_branch .Lr5_done
.Lr5_high:
	s_cmp_lt_u32 s99, 4
	s_cbranch_scc1 .Lr5_done
	s_sub_i32 s100, s100, 16
	s_lshl_b32 s100, s100, 2
	s_add_i32 s100, s100, s99
	s_add_i32 s21, s100, 0x1ffc
.Lr5_done:
	s_branch .LBB0_116
.LBB0_115:
	s_add_i32 s30, s30, 1
	s_add_i32 s22, s22, s59
	s_cmp_eq_u32 s30, 6
	s_cbranch_scc1 .LBB0_135
	v_readlane_b32 s98, v248, 32
	s_nop 0
	s_cmp_lt_u32 s98, 0x80
	s_cbranch_scc1 .Lrow_low
	s_cmp_eq_u32 s30, 5
	s_cbranch_scc0 .LBB0_116
	s_mul_i32 s10, s59, 3
	s_add_i32 s10, s10, s66
	s_addk_i32 s10, 0xff80
	s_branch .LBB0_116
